# same as the P6-epilogue version plus two wait states restored between a v_add_co and its v_addc in the prep loop (spacing the compiler keeps everywhere else)
# baseline (speedup 1.0000x reference)
.LBB0_540:
	s_add_i32 s14, s49, s48
	v_mad_i64_i32 v[28:29], s[4:5], s14, v100, v[26:27]
	v_add_co_u32_e32 v60, vcc, 0x1000, v28
	s_add_i32 s4, s14, 1
	s_nop 0
	v_addc_co_u32_e32 v61, vcc, 0, v29, vcc
	global_load_dword v117, v[60:61], off nt
	global_load_dword v120, v[28:29], off offset:2048 nt
	global_load_dword v121, v[28:29], off nt
	v_mad_i64_i32 v[28:29], s[4:5], s4, v100, v[26:27]
	v_add_co_u32_e32 v60, vcc, 0x1000, v28
	s_add_i32 s4, s14, 2
	s_nop 0
	v_addc_co_u32_e32 v61, vcc, 0, v29, vcc
	global_load_dword v118, v[60:61], off nt
	global_load_dword v122, v[28:29], off offset:2048 nt
	global_load_dword v123, v[28:29], off nt
	v_mad_i64_i32 v[28:29], s[4:5], s4, v100, v[26:27]
	v_add_co_u32_e32 v60, vcc, 0x1000, v28
	s_add_i32 s4, s14, 3
	s_nop 0
	v_addc_co_u32_e32 v61, vcc, 0, v29, vcc
	global_load_dword v119, v[60:61], off nt
	global_load_dword v125, v[28:29], off offset:2048 nt
	global_load_dword v126, v[28:29], off nt
	v_mad_i64_i32 v[28:29], s[4:5], s4, v100, v[26:27]
	v_add_co_u32_e32 v60, vcc, 0x1000, v28
	s_add_i32 s4, s14, 4
	s_nop 0
	v_addc_co_u32_e32 v61, vcc, 0, v29, vcc
	global_load_dword v124, v[60:61], off nt
	global_load_dword v129, v[28:29], off offset:2048 nt
	global_load_dword v130, v[28:29], off nt
	v_mad_i64_i32 v[28:29], s[4:5], s4, v100, v[26:27]
	v_add_co_u32_e32 v60, vcc, 0x1000, v28
	s_add_i32 s4, s14, 5
	s_nop 0
	v_addc_co_u32_e32 v61, vcc, 0, v29, vcc
	global_load_dword v127, v[60:61], off nt
	global_load_dword v131, v[28:29], off offset:2048 nt
	global_load_dword v132, v[28:29], off nt
	v_mad_i64_i32 v[28:29], s[4:5], s4, v100, v[26:27]
	v_add_co_u32_e32 v60, vcc, 0x1000, v28
	s_add_i32 s14, s14, 6
	s_nop 0
	v_addc_co_u32_e32 v61, vcc, 0, v29, vcc
	global_load_dword v128, v[60:61], off nt
	global_load_dword v133, v[28:29], off offset:2048 nt
	global_load_dword v135, v[28:29], off nt
	v_mad_i64_i32 v[28:29], s[4:5], s14, v100, v[26:27]
	s_or_b32 s4, s6, 7
	v_add_co_u32_e32 v60, vcc, 0x1000, v28
	s_add_i32 s4, s4, s48
	s_nop 0
	v_addc_co_u32_e32 v61, vcc, 0, v29, vcc
	v_mad_i64_i32 v[26:27], s[4:5], s4, v100, v[26:27]
	global_load_dword v134, v[60:61], off nt
	global_load_dword v137, v[28:29], off offset:2048 nt
	global_load_dword v138, v[28:29], off nt
	v_add_co_u32_e32 v28, vcc, 0x1000, v26
	s_nop 1
	v_addc_co_u32_e32 v29, vcc, 0, v27, vcc
	global_load_dword v136, v[28:29], off nt
	global_load_dword v142, v[26:27], off offset:2048 nt
	global_load_dword v143, v[26:27], off nt
